# v36 plus grid barrier with flat release: XCC last arriver adds to the top counter without waiting, every workgroup polls that one word (drops generation words and two hops)
# baseline (speedup 1.0000x reference)
.LBB0_95:
	s_getreg_b32 s98, hwreg(HW_REG_XCC_ID, 0, 4)
	v_mov_b32_e32 v1, 0x21160
	ds_read_b64 v[2:3], v1
	s_lshl_b32 s98, s98, 8
	s_add_u32 s100, s54, 0x5400
	s_addc_u32 s101, s55, 0
	v_mov_b32_e32 v4, s98
	v_mov_b32_e32 v5, 1
	global_atomic_add v4, v4, v5, s[100:101] sc0
	s_waitcnt lgkmcnt(0)
	v_mul_u32_u24_e32 v2, 1, v2
	v_mul_u32_u24_e32 v3, 1, v3
	s_waitcnt vmcnt(0)
	v_add_u32_e32 v4, 1, v4
	v_cmp_eq_u32_e32 vcc, v4, v2
	s_and_saveexec_b64 s[98:99], vcc
	s_cbranch_execz .Lgbar1_poll
	buffer_wbl2 sc1
	s_waitcnt vmcnt(0)
	v_mov_b32_e32 v4, 0x7400
	global_atomic_add v4, v5, s[54:55]
.Lgbar1_poll:
	s_or_b64 exec, exec, s[98:99]
	v_readfirstlane_b32 s98, v3
	v_mov_b32_e32 v4, 0x7400
	s_mov_b32 s99, 0
.Lgbar1_spin:
	global_load_dword v5, v4, s[54:55] sc1
	s_waitcnt vmcnt(0)
	v_readfirstlane_b32 s100, v5
	s_cmp_ge_u32 s100, s98
	s_cbranch_scc1 .Lgbar1_done
	s_add_i32 s99, s99, 1
	s_cmp_gt_u32 s99, 0x40000
	s_cbranch_scc1 .Lgbar1_done
	s_sleep 1
	s_branch .Lgbar1_spin
.Lgbar1_done:
	buffer_inv sc1
	s_waitcnt vmcnt(0)
.LBB0_131:
	s_or_b64 exec, exec, s[6:7]
	v_mov_b32_e32 v10, v0
	s_cmpk_lt_i32 s38, 0x1e0
	s_waitcnt lgkmcnt(0)
	s_barrier
	s_cselect_b64 s[4:5], -1, 0
	s_cmpk_gt_i32 s38, 0x1df
	v_readfirstlane_b32 s0, v10
	s_cbranch_scc1 .LBB0_133
	s_ashr_i32 s1, s38, 31
	s_lshr_b32 s1, s1, 29
	s_add_i32 s1, s38, s1
	s_ashr_i32 s3, s1, 3
	s_and_b32 s1, s1, -8
	s_sub_i32 s1, s38, s1
	s_cmp_lt_i32 s1, 0
	s_cselect_b32 s6, 61, 60
	s_mul_i32 s1, s1, s6
	s_add_i32 s1, s1, s3
	s_mul_hi_i32 s3, s1, 0x88888889
	s_add_i32 s3, s3, s1
	s_lshr_b32 s6, s3, 31
	s_ashr_i32 s3, s3, 5
	s_add_i32 s3, s3, s6
	s_mul_i32 s6, s3, 6
	s_mul_i32 s3, s3, 60
	s_sub_i32 s1, s1, s3
	s_bfe_i32 s3, s1, 0x80000
	s_mul_i32 s3, s3, 43
	s_bfe_u32 s7, s3, 0x1000f
	s_bfe_u32 s3, s3, 0x80008
	s_add_i32 s3, s3, s7
	s_mul_i32 s7, s3, 6
	s_sub_i32 s1, s1, s7
	s_sext_i32_i8 s1, s1
	s_add_i32 s70, s6, s1
	s_sext_i32_i8 s8, s3

.LBB0_236:
	s_getreg_b32 s98, hwreg(HW_REG_XCC_ID, 0, 4)
	v_mov_b32_e32 v1, 0x21160
	ds_read_b64 v[2:3], v1
	s_lshl_b32 s98, s98, 8
	s_add_u32 s100, s54, 0x5400
	s_addc_u32 s101, s55, 0
	v_mov_b32_e32 v4, s98
	v_mov_b32_e32 v5, 1
	global_atomic_add v4, v4, v5, s[100:101] sc0
	s_waitcnt lgkmcnt(0)
	v_mul_u32_u24_e32 v2, 2, v2
	v_mul_u32_u24_e32 v3, 2, v3
	s_waitcnt vmcnt(0)
	v_add_u32_e32 v4, 1, v4
	v_cmp_eq_u32_e32 vcc, v4, v2
	s_and_saveexec_b64 s[98:99], vcc
	s_cbranch_execz .Lgbar2_poll
	buffer_wbl2 sc1
	s_waitcnt vmcnt(0)
	v_mov_b32_e32 v4, 0x7400
	global_atomic_add v4, v5, s[54:55]

.Lgbar2_done:
	buffer_inv sc1
	s_waitcnt vmcnt(0)
.LBB0_272:
	s_or_b64 exec, exec, s[6:7]
	s_add_u32 s92, s54, 0xa000000
	s_addc_u32 s93, s55, 0
	s_add_u32 s82, s54, 0x2400
	s_addc_u32 s83, s55, 0
	s_add_u32 s80, s54, 0xd000000
	v_mov_b32_e32 v130, v0
	s_addc_u32 s81, s55, 0
	s_waitcnt lgkmcnt(0)
	s_barrier
	s_mov_b64 s[4:5], -1
	s_andn2_b64 vcc, exec, s[16:17]
	v_bfe_u32 v88, v130, 4, 2
	v_and_b32_e32 v135, 15, v130
	v_lshlrev_b32_e32 v89, 4, v130
	v_ashrrev_i32_e32 v1, 4, v130
	v_lshlrev_b32_e32 v141, 2, v130
	v_cmp_eq_u32_e64 s[34:35], 0, v130
	s_cbranch_vccnz .LBB0_279
	v_add_u32_e32 v4, 0x200, v130
	v_and_b32_e32 v66, 0xf0, v89
	v_ashrrev_i32_e32 v90, 4, v4
	v_add_u32_e32 v4, 0x400, v130
	s_add_i32 s0, 0, 0x11000
	v_and_b32_e32 v7, 12, v141
	v_ashrrev_i32_e32 v91, 4, v4
	v_add_u32_e32 v4, 0x600, v130
	v_add_u32_e32 v5, s0, v66
	v_lshlrev_b32_e32 v93, 1, v7
	v_sub_u32_e32 v7, 0xff, v1
	s_movk_i32 s0, 0x110
	v_ashrrev_i32_e32 v92, 4, v4
	v_add_u32_e32 v4, 0, v66
	v_cvt_f32_i32_e32 v94, v7
	v_mul_lo_u32 v7, v1, s0
	v_add_u32_e32 v96, v4, v7
	v_add_u32_e32 v97, v5, v7
	v_sub_u32_e32 v7, 0xff, v90
	v_cvt_f32_i32_e32 v98, v7
	v_mul_lo_u32 v7, v90, s0
	v_add_u32_e32 v100, v4, v7
	v_add_u32_e32 v101, v5, v7
	v_sub_u32_e32 v7, 0xff, v91
	v_cvt_f32_i32_e32 v102, v7
	v_mul_lo_u32 v7, v91, s0
	v_add_u32_e32 v104, v4, v7
	v_add_u32_e32 v105, v5, v7
	v_sub_u32_e32 v7, 0xff, v92
	v_cvt_f32_i32_e32 v106, v7
	v_mul_lo_u32 v7, v92, s0
	v_add_u32_e32 v108, v4, v7
	v_add_u32_e32 v109, v5, v7
	v_add_u32_e32 v4, 0x80, v1
	v_sub_u32_e32 v5, 0x7f, v1
	v_cvt_f32_i32_e32 v112, v5
	v_cvt_f32_i32_e32 v113, v4
	v_add_u32_e32 v4, 0x80, v90
	v_sub_u32_e32 v5, 0x7f, v90
	s_lshl_b32 s3, s38, 1
	v_cvt_f32_i32_e32 v114, v5
	v_cvt_f32_i32_e32 v115, v4
	v_add_u32_e32 v4, 0x80, v91
	v_sub_u32_e32 v5, 0x7f, v91
	s_add_i32 s36, s3, 0xfffffec0
	v_cvt_f32_i32_e32 v116, v5
	v_cvt_f32_i32_e32 v117, v4
	v_add_u32_e32 v4, 0x80, v92
	v_sub_u32_e32 v5, 0x7f, v92
	s_bfe_u32 s18, s38, 0x20002
	v_readlane_b32 s0, v242, 0
	v_bfe_u32 v6, v130, 2, 2
	v_cvt_f32_i32_e32 v95, v1
	v_cvt_f32_i32_e32 v99, v90
	v_cvt_f32_i32_e32 v103, v91
	v_cvt_f32_i32_e32 v107, v92
	v_cvt_f32_i32_e32 v118, v5
	v_cvt_f32_i32_e32 v119, v4
	s_lshl_b32 s16, s18, 2
	v_readlane_b32 s4, v242, 4
	v_mov_b32_e32 v67, 0
	v_lshl_or_b32 v6, v88, 3, v6
	v_lshlrev_b32_e32 v4, 7, v135
	v_readlane_b32 s5, v242, 5
	s_add_u32 s16, s4, s16
	s_mov_b32 s73, 0
	v_lshl_add_u64 v[2:3], s[68:69], 0, v[66:67]
	v_mul_u32_u24_e32 v110, 0x110, v6
	v_lshlrev_b32_e32 v6, 2, v88
	v_or_b32_e32 v8, 0x800, v4
	v_or_b32_e32 v10, 0x1000, v4
	v_or_b32_e32 v12, 0x1800, v4
	v_or_b32_e32 v14, 0x2000, v4
	v_or_b32_e32 v16, 0x2800, v4
	v_or_b32_e32 v18, 0x3000, v4
	v_or_b32_e32 v20, 0x3800, v4
	v_readlane_b32 s1, v242, 1
	v_readlane_b32 s10, v242, 10
	v_readlane_b32 s11, v242, 11
	s_addc_u32 s17, s5, 0
	s_lshl_b32 s72, s18, 8
	v_add3_u32 v111, 0, v93, v110
	v_lshl_add_u64 v[68:69], v[2:3], 0, s[72:73]
	s_mov_b64 s[18:19], -1
	s_mov_b32 s0, 0xbfb8aa3b
	s_mov_b32 s1, 0x42ce8ed0
	s_mov_b32 s10, 0xc2b17218
	s_mov_b32 s11, 0x7f800000
	s_mov_b32 s24, 0x3f2aaaab
	v_mov_b32_e32 v120, 0x3ecc95a3
	s_mov_b32 s25, 0x3f317218
	s_mov_b32 s26, 0x33800000
	s_movk_i32 s27, 0x1400
	s_mov_b32 s28, 0x8800
	v_lshlrev_b32_e32 v70, 1, v6
	v_lshlrev_b32_e32 v72, 1, v4
	v_lshlrev_b32_e32 v74, 1, v8
	v_lshlrev_b32_e32 v76, 1, v10
	v_lshlrev_b32_e32 v66, 1, v12
	v_lshlrev_b32_e32 v78, 1, v14
	v_lshlrev_b32_e32 v80, 1, v16
	v_lshlrev_b32_e32 v82, 1, v18
	v_lshlrev_b32_e32 v84, 1, v20
	v_mov_b32_e32 v121, 0x7f800000
	v_mov_b32_e32 v86, 0x3f317218
	v_mov_b32_e32 v71, v67
	v_mov_b32_e32 v73, v67
	v_mov_b32_e32 v75, v67
	v_mov_b32_e32 v77, v67
	s_mov_b32 s5, 0
	v_readlane_b32 s2, v242, 2
	v_readlane_b32 s3, v242, 3
	v_readlane_b32 s6, v242, 6
	v_readlane_b32 s7, v242, 7
	v_readlane_b32 s8, v242, 8
	v_readlane_b32 s9, v242, 9
	v_readlane_b32 s12, v242, 12
	v_readlane_b32 s13, v242, 13
	v_readlane_b32 s14, v242, 14
	v_readlane_b32 s15, v242, 15
	s_branch .LBB0_275

.LBB0_324:
	s_getreg_b32 s98, hwreg(HW_REG_XCC_ID, 0, 4)
	v_mov_b32_e32 v1, 0x21160
	ds_read_b64 v[2:3], v1
	s_lshl_b32 s98, s98, 8
	s_add_u32 s100, s54, 0x5400
	s_addc_u32 s101, s55, 0
	v_mov_b32_e32 v4, s98
	v_mov_b32_e32 v5, 1
	global_atomic_add v4, v4, v5, s[100:101] sc0
	s_waitcnt lgkmcnt(0)
	v_mul_u32_u24_e32 v2, 3, v2
	v_mul_u32_u24_e32 v3, 3, v3
	s_waitcnt vmcnt(0)
	v_add_u32_e32 v4, 1, v4
	v_cmp_eq_u32_e32 vcc, v4, v2
	s_and_saveexec_b64 s[98:99], vcc
	s_cbranch_execz .Lgbar3_poll
	buffer_wbl2 sc1
	s_waitcnt vmcnt(0)
	v_mov_b32_e32 v4, 0x7400
	global_atomic_add v4, v5, s[54:55]

.Lgbar3_done:
	buffer_inv sc1
	s_waitcnt vmcnt(0)
.LBB0_360:
	s_or_b64 exec, exec, s[6:7]
	s_add_u32 s60, s54, 0xb800000
	s_addc_u32 s61, s55, 0
	s_cmpk_gt_i32 s38, 0x7f
	s_waitcnt lgkmcnt(0)
	s_barrier
	s_cbranch_scc0 .LBB0_365
	s_cmpk_lt_u32 s38, 0x80
	s_mov_b64 s[14:15], 0
	s_cbranch_scc0 .LBB0_366
	s_and_b32 s0, s38, 3
	s_lshl_b32 s1, s0, 2
	v_readlane_b32 s16, v242, 0
	v_mov_b32_e32 v4, v0
	v_mov_b32_e32 v1, s1
	v_readlane_b32 s20, v242, 4
	v_readlane_b32 s21, v242, 5
	s_nop 4
	global_load_dword v2, v1, s[20:21]
	global_load_dword v5, v1, s[20:21] offset:16
	s_mov_b32 s7, 0xbfb8aa3b
	s_mov_b32 s8, 0x42ce8ed0
	s_mov_b32 s9, 0xc2b17218
	v_mov_b32_e32 v8, 0x7f800000
	s_mov_b32 s10, 0x3f2aaaab
	s_mov_b32 s6, 0x3f317218
	v_mov_b32_e32 v9, 0x3ecc95a3
	s_mov_b32 s4, 0x7f800000
	s_mov_b32 s5, 0x33800000
	v_mov_b32_e32 v10, 0x3f2aaada
	s_lshl_b32 s1, s38, 6
	s_add_i32 s1, s1, 0x7fffe000
	v_readfirstlane_b32 s11, v4
	s_and_b32 s3, s1, 0x7fffff00
	s_ashr_i32 s1, s11, 6
	v_and_b32_e32 v12, 15, v4
	s_lshl_b32 s16, s0, 8
	v_readlane_b32 s18, v242, 2
	v_mov_b32_e32 v3, 0
	s_movk_i32 s18, 0x1400
	v_readlane_b32 s17, v242, 1
	s_mov_b32 s17, 0
	v_bfe_u32 v13, v4, 4, 2
	v_and_b32_e32 v1, 63, v4
	v_readlane_b32 s19, v242, 3
	v_readlane_b32 s22, v242, 6
	v_readlane_b32 s23, v242, 7
	v_readlane_b32 s24, v242, 8
	v_readlane_b32 s25, v242, 9
	v_readlane_b32 s26, v242, 10
	s_movk_i32 s19, 0xffee
	s_movk_i32 s20, 0xffed
	s_movk_i32 s21, 0xffdf
	s_movk_i32 s22, 0xffde
	s_movk_i32 s23, 0xffdd
	s_movk_i32 s24, 0xffcf
	s_movk_i32 s25, 0xffce
	s_movk_i32 s26, 0xffcd
	v_mov_b32_e32 v34, v3
	v_mov_b32_e32 v35, v3
	v_mov_b32_e32 v36, v3
	v_mov_b32_e32 v37, v3
	v_mov_b32_e32 v38, v3
	v_mov_b32_e32 v39, v3
	v_mov_b32_e32 v40, v3
	v_mov_b32_e32 v41, v3
	v_mov_b32_e32 v50, v3
	v_mov_b32_e32 v51, v3
	v_mov_b32_e32 v52, v3
	v_mov_b32_e32 v53, v3
	v_mov_b32_e32 v66, v3
	v_mov_b32_e32 v67, v3
	v_mov_b32_e32 v68, v3
	v_mov_b32_e32 v69, v3
	v_mov_b32_e32 v25, v3
	v_mov_b32_e32 v26, v3
	v_mov_b32_e32 v27, v3
	v_mov_b32_e32 v28, v3
	v_mov_b32_e32 v29, v3
	v_mov_b32_e32 v30, v3
	v_mov_b32_e32 v31, v3
	v_mov_b32_e32 v32, v3
	v_mov_b32_e32 v33, v3
	v_mov_b32_e32 v62, v3
	v_mov_b32_e32 v63, v3
	v_mov_b32_e32 v64, v3
	v_mov_b32_e32 v65, v3
	v_mov_b32_e32 v70, v3
	v_mov_b32_e32 v71, v3
	v_mov_b32_e32 v72, v3
	v_mov_b32_e32 v73, v3
	v_mov_b32_e32 v74, v3
	v_mov_b32_e32 v75, v3
	v_mov_b32_e32 v76, v3
	v_mov_b32_e32 v77, v3
	v_mov_b32_e32 v94, v3
	v_mov_b32_e32 v95, v3
	v_mov_b32_e32 v96, v3
	s_waitcnt vmcnt(1)
	v_mul_f32_e32 v6, 0xbfb8aa3b, v2
	v_fma_f32 v11, v2, s7, -v6
	v_rndne_f32_e32 v14, v6
	v_fmac_f32_e32 v11, 0xb2a5705f, v2
	v_sub_f32_e32 v6, v6, v14
	v_add_f32_e32 v6, v6, v11
	v_cvt_i32_f32_e32 v14, v14
	v_exp_f32_e32 v6, v6
	s_waitcnt vmcnt(0)
	v_mul_f32_e32 v7, 0xbfb8aa3b, v5
	v_cmp_nlt_f32_e32 vcc, s8, v2
	v_fma_f32 v15, v5, s7, -v7
	v_ldexp_f32 v6, v6, v14
	v_rndne_f32_e32 v16, v7
	v_cndmask_b32_e32 v6, 0, v6, vcc
	v_cmp_ngt_f32_e32 vcc, s9, v2
	v_fmac_f32_e32 v15, 0xb2a5705f, v5
	v_sub_f32_e32 v7, v7, v16
	v_cndmask_b32_e32 v2, v8, v6, vcc
	v_add_f32_e32 v7, v7, v15
	v_add_f32_e32 v14, 1.0, v2
	v_cvt_i32_f32_e32 v11, v16
	v_exp_f32_e32 v15, v7
	v_add_f32_e32 v16, -1.0, v14
	v_frexp_mant_f32_e32 v17, v14
	v_cvt_f64_f32_e32 v[6:7], v14
	v_sub_f32_e32 v18, v16, v14
	v_frexp_exp_i32_f64_e32 v6, v[6:7]
	v_cmp_gt_f32_e32 vcc, s10, v17
	v_sub_f32_e32 v16, v2, v16
	v_add_f32_e32 v7, 1.0, v18
	v_subbrev_co_u32_e32 v6, vcc, 0, v6, vcc
	v_add_f32_e32 v7, v16, v7
	v_sub_u32_e32 v16, 0, v6
	v_cvt_f32_i32_e32 v6, v6
	v_ldexp_f32 v14, v14, v16
	v_ldexp_f32 v7, v7, v16
	v_add_f32_e32 v16, -1.0, v14
	v_add_f32_e32 v17, 1.0, v14
	v_add_f32_e32 v18, 1.0, v16
	v_add_f32_e32 v19, -1.0, v17
	v_sub_f32_e32 v18, v14, v18
	v_sub_f32_e32 v14, v14, v19
	v_mul_f32_e32 v19, 0x3f317218, v6
	v_add_f32_e32 v18, v7, v18
	v_add_f32_e32 v7, v7, v14
	v_fma_f32 v14, v6, s6, -v19
	v_add_f32_e32 v20, v16, v18
	v_add_f32_e32 v21, v17, v7
	v_fmac_f32_e32 v14, 0xb102e308, v6
	v_sub_f32_e32 v6, v16, v20
	v_sub_f32_e32 v16, v17, v21
	v_rcp_f32_e32 v17, v21
	v_add_f32_e32 v22, v19, v14
	v_add_f32_e32 v7, v7, v16
	v_sub_f32_e32 v16, v22, v19
	v_sub_f32_e32 v14, v14, v16
	v_mul_f32_e32 v16, v20, v17
	v_add_f32_e32 v6, v18, v6
	v_mul_f32_e32 v18, v21, v16
	v_fma_f32 v19, v16, v21, -v18
	v_fmac_f32_e32 v19, v16, v7
	v_add_f32_e32 v23, v18, v19
	v_sub_f32_e32 v24, v20, v23
	v_sub_f32_e32 v18, v23, v18
	v_sub_f32_e32 v20, v20, v24
	v_sub_f32_e32 v18, v18, v19
	v_sub_f32_e32 v19, v20, v23
	v_add_f32_e32 v6, v6, v19
	v_add_f32_e32 v6, v18, v6
	v_add_f32_e32 v18, v24, v6
	v_mul_f32_e32 v19, v17, v18
	v_sub_f32_e32 v20, v24, v18
	v_mul_f32_e32 v23, v21, v19
	v_add_f32_e32 v6, v6, v20
	v_add_f32_e32 v20, v16, v19
	v_fma_f32 v21, v19, v21, -v23
	v_sub_f32_e32 v16, v20, v16
	v_fmac_f32_e32 v21, v19, v7
	v_sub_f32_e32 v7, v19, v16
	v_add_f32_e32 v16, v23, v21
	v_sub_f32_e32 v19, v16, v23
	v_sub_f32_e32 v23, v18, v16
	v_sub_f32_e32 v18, v18, v23
	v_sub_f32_e32 v16, v18, v16
	v_sub_f32_e32 v19, v19, v21
	v_add_f32_e32 v6, v6, v16
	v_add_f32_e32 v6, v19, v6
	v_add_f32_e32 v6, v23, v6
	v_mul_f32_e32 v6, v17, v6
	v_add_f32_e32 v6, v7, v6
	v_add_f32_e32 v7, v20, v6
	v_mul_f32_e32 v16, v7, v7
	v_fmamk_f32 v19, v16, 0x3e9b6dac, v9
	v_sub_f32_e32 v17, v7, v20
	v_ldexp_f32 v18, v7, 1
	v_mul_f32_e32 v7, v7, v16
	v_fmaak_f32 v16, v16, v19, 0x3f2aaada
	v_mul_f32_e32 v7, v7, v16
	v_add_f32_e32 v16, v18, v7
	v_sub_f32_e32 v6, v6, v17
	v_sub_f32_e32 v17, v16, v18
	v_ldexp_f32 v6, v6, 1
	v_sub_f32_e32 v7, v7, v17
	v_add_f32_e32 v6, v6, v7
	v_add_f32_e32 v7, v16, v6
	v_sub_f32_e32 v16, v7, v16
	v_add_f32_e32 v17, v22, v7
	v_sub_f32_e32 v6, v6, v16
	v_sub_f32_e32 v16, v17, v22
	v_sub_f32_e32 v18, v17, v16
	v_sub_f32_e32 v7, v7, v16
	v_add_f32_e32 v16, v14, v6
	v_sub_f32_e32 v18, v22, v18
	v_sub_f32_e32 v19, v16, v14
	v_add_f32_e32 v7, v7, v18
	v_sub_f32_e32 v18, v16, v19
	v_sub_f32_e32 v6, v6, v19
	v_sub_f32_e32 v14, v14, v18
	v_add_f32_e32 v7, v16, v7
	v_add_f32_e32 v6, v6, v14
	v_add_f32_e32 v14, v17, v7
	v_sub_f32_e32 v16, v14, v17
	v_sub_f32_e32 v7, v7, v16
	v_add_f32_e32 v6, v6, v7
	v_add_f32_e32 v6, v14, v6
	v_cmp_neq_f32_e32 vcc, s4, v2
	v_mov_b32_e32 v21, v3
	v_mov_b32_e32 v22, v3
	v_cndmask_b32_e32 v6, v8, v6, vcc
	v_cmp_lt_f32_e64 vcc, |v2|, s5
	v_mov_b32_e32 v23, v3
	v_mov_b32_e32 v24, v3
	v_cndmask_b32_e32 v2, v6, v2, vcc
	v_mul_f32_e32 v140, 0xbfb8aa3b, v2
	v_ldexp_f32 v2, v15, v11
	v_cmp_nlt_f32_e32 vcc, s8, v5
	s_mul_i32 s8, s1, 0x1200
	v_exp_f32_e64 v145, -v140
	v_cndmask_b32_e32 v2, 0, v2, vcc
	v_cmp_ngt_f32_e32 vcc, s9, v5
	v_mov_b32_e32 v97, v3
	v_readlane_b32 s27, v242, 11
	v_cndmask_b32_e32 v2, v8, v2, vcc
	v_add_f32_e32 v5, 1.0, v2
	v_add_f32_e32 v6, -1.0, v5
	v_sub_f32_e32 v7, v6, v5
	v_add_f32_e32 v7, 1.0, v7
	v_sub_f32_e32 v6, v2, v6
	v_add_f32_e32 v11, v6, v7
	v_frexp_mant_f32_e32 v14, v5
	v_cvt_f64_f32_e32 v[6:7], v5
	v_frexp_exp_i32_f64_e32 v6, v[6:7]
	v_cmp_gt_f32_e32 vcc, s10, v14
	v_readlane_b32 s28, v242, 12
	v_readlane_b32 s29, v242, 13
	v_subbrev_co_u32_e32 v6, vcc, 0, v6, vcc
	v_sub_u32_e32 v7, 0, v6
	v_ldexp_f32 v5, v5, v7
	v_ldexp_f32 v7, v11, v7
	v_add_f32_e32 v11, -1.0, v5
	v_add_f32_e32 v16, 1.0, v5
	v_add_f32_e32 v14, 1.0, v11
	v_add_f32_e32 v17, -1.0, v16
	v_sub_f32_e32 v14, v5, v14
	v_sub_f32_e32 v5, v5, v17
	v_add_f32_e32 v5, v7, v5
	v_add_f32_e32 v14, v7, v14
	v_add_f32_e32 v7, v16, v5
	v_rcp_f32_e32 v17, v7
	v_add_f32_e32 v15, v11, v14
	v_sub_f32_e32 v11, v11, v15
	v_add_f32_e32 v11, v14, v11
	v_sub_f32_e32 v14, v16, v7
	v_add_f32_e32 v5, v5, v14
	v_mul_f32_e32 v14, v15, v17
	v_mul_f32_e32 v16, v7, v14
	v_fma_f32 v18, v14, v7, -v16
	v_fmac_f32_e32 v18, v14, v5
	v_add_f32_e32 v19, v16, v18
	v_sub_f32_e32 v20, v15, v19
	v_sub_f32_e32 v15, v15, v20
	v_sub_f32_e32 v16, v19, v16
	v_sub_f32_e32 v15, v15, v19
	v_add_f32_e32 v11, v11, v15
	v_sub_f32_e32 v15, v16, v18
	v_add_f32_e32 v11, v15, v11
	v_add_f32_e32 v15, v20, v11
	v_mul_f32_e32 v16, v17, v15
	v_mul_f32_e32 v18, v7, v16
	v_fma_f32 v7, v16, v7, -v18
	v_fmac_f32_e32 v7, v16, v5
	v_sub_f32_e32 v5, v20, v15
	v_add_f32_e32 v5, v11, v5
	v_add_f32_e32 v11, v18, v7
	v_sub_f32_e32 v19, v15, v11
	v_sub_f32_e32 v15, v15, v19
	v_sub_f32_e32 v18, v11, v18
	v_sub_f32_e32 v11, v15, v11
	v_add_f32_e32 v5, v5, v11
	v_sub_f32_e32 v7, v18, v7
	v_add_f32_e32 v5, v7, v5
	v_add_f32_e32 v7, v14, v16
	v_add_f32_e32 v5, v19, v5
	v_sub_f32_e32 v11, v7, v14
	v_mul_f32_e32 v5, v17, v5
	v_sub_f32_e32 v11, v16, v11
	v_add_f32_e32 v5, v11, v5
	v_cvt_f32_i32_e32 v6, v6
	v_add_f32_e32 v11, v7, v5
	v_mul_f32_e32 v14, v11, v11
	v_fmac_f32_e32 v9, 0x3e9b6dac, v14
	v_fmac_f32_e32 v10, v14, v9
	v_mul_f32_e32 v9, 0x3f317218, v6
	v_fma_f32 v15, v6, s6, -v9
	v_fmac_f32_e32 v15, 0xb102e308, v6
	v_sub_f32_e32 v6, v11, v7
	v_sub_f32_e32 v5, v5, v6
	v_add_f32_e32 v6, v9, v15
	v_sub_f32_e32 v7, v6, v9
	v_ldexp_f32 v9, v11, 1
	v_mul_f32_e32 v11, v11, v14
	v_mul_f32_e32 v10, v11, v10
	v_add_f32_e32 v11, v9, v10
	v_sub_f32_e32 v9, v11, v9
	v_ldexp_f32 v5, v5, 1
	v_sub_f32_e32 v9, v10, v9
	v_add_f32_e32 v5, v5, v9
	v_add_f32_e32 v9, v11, v5
	v_sub_f32_e32 v10, v9, v11
	v_sub_f32_e32 v5, v5, v10
	v_add_f32_e32 v10, v6, v9
	v_sub_f32_e32 v11, v10, v6
	v_sub_f32_e32 v14, v10, v11
	v_sub_f32_e32 v7, v15, v7
	v_sub_f32_e32 v6, v6, v14
	v_sub_f32_e32 v9, v9, v11
	v_add_f32_e32 v6, v9, v6
	v_add_f32_e32 v9, v7, v5
	v_sub_f32_e32 v11, v9, v7
	v_sub_f32_e32 v14, v9, v11
	v_sub_f32_e32 v7, v7, v14
	v_sub_f32_e32 v5, v5, v11
	v_add_f32_e32 v6, v9, v6
	v_add_f32_e32 v5, v5, v7
	v_add_f32_e32 v7, v10, v6
	v_sub_f32_e32 v9, v7, v10
	v_sub_f32_e32 v6, v6, v9
	v_add_f32_e32 v5, v5, v6
	v_add_f32_e32 v5, v7, v5
	v_cmp_neq_f32_e32 vcc, s4, v2
	s_lshl_b32 s4, s0, 7
	v_ashrrev_i32_e32 v15, 4, v4
	v_cndmask_b32_e32 v5, v8, v5, vcc
	v_cmp_lt_f32_e64 vcc, |v2|, s5
	s_lshl_b32 s5, s1, 5
	s_add_u32 s0, s68, s16
	v_cndmask_b32_e32 v2, v5, v2, vcc
	v_mul_f32_e32 v149, 0xbfb8aa3b, v2
	v_mul_f32_e32 v2, 0x80000000, v140
	v_exp_f32_e32 v147, v2
	v_mul_f32_e32 v2, 0, v149
	v_exp_f32_e32 v148, v2
	v_mul_f32_e32 v2, -2.0, v140
	v_exp_f32_e32 v143, v2
	v_add_f32_e32 v2, v149, v149
	v_exp_f32_e32 v144, v2
	v_mul_f32_e32 v2, 0xc0400000, v140
	v_exp_f32_e32 v142, v2
	v_mul_f32_e32 v2, 0x40400000, v149
	v_exp_f32_e32 v141, v2
	v_or_b32_e32 v2, s5, v12
	v_add_u32_e32 v5, s3, v2
	s_addc_u32 s1, s69, 0
	v_and_b32_e32 v2, 48, v4
	v_lshl_add_u64 v[6:7], s[0:1], 0, v[2:3]
	v_mad_i64_i32 v[8:9], s[6:7], v5, s18, v[6:7]
	v_or_b32_e32 v5, 16, v5
	v_mad_i64_i32 v[6:7], s[6:7], v5, s18, v[6:7]
	global_load_dwordx4 v[90:93], v[8:9], off
	global_load_dwordx4 v[86:89], v[8:9], off offset:64
	global_load_dwordx4 v[82:85], v[8:9], off offset:128
	global_load_dwordx4 v[78:81], v[8:9], off offset:192
	global_load_dwordx4 v[58:61], v[6:7], off
	global_load_dwordx4 v[54:57], v[6:7], off offset:64
	global_load_dwordx4 v[46:49], v[6:7], off offset:128
	global_load_dwordx4 v[42:45], v[6:7], off offset:192
	v_add_u32_e32 v16, s3, v15
	v_mov_b64_e32 v[6:7], s[68:69]
	v_mad_i64_i32 v[8:9], s[6:7], v16, s18, v[6:7]
	v_lshlrev_b32_e32 v10, 4, v4
	v_lshl_add_u64 v[8:9], v[8:9], 0, s[16:17]
	v_and_b32_e32 v10, 0xf0, v10
	v_mov_b32_e32 v11, v3
	v_lshl_add_u64 v[8:9], v[8:9], 0, v[10:11]
	global_load_dwordx4 v[98:101], v[8:9], off offset:1024
	global_load_dwordx4 v[102:105], v[8:9], off offset:2048
	v_add_u32_e32 v8, 0x200, v4
	v_ashrrev_i32_e32 v8, 4, v8
	v_add_u32_e32 v9, s3, v8
	v_mad_i64_i32 v[6:7], s[6:7], v9, s18, v[6:7]
	v_lshl_add_u64 v[6:7], v[6:7], 0, s[16:17]
	v_lshl_add_u64 v[6:7], v[6:7], 0, v[10:11]
	global_load_dwordx4 v[106:109], v[6:7], off offset:1024
	global_load_dwordx4 v[110:113], v[6:7], off offset:2048
	v_exp_f32_e32 v146, v149
	v_lshlrev_b32_e32 v14, 3, v13
	v_lshlrev_b32_e32 v5, 3, v4
	v_lshlrev_b32_e32 v13, 2, v13
	v_bfe_u32 v4, v4, 2, 2
	s_add_i32 s6, s8, 0
	v_add_u32_e32 v6, 0, v10
	v_add_u32_e32 v7, 0, v2
	v_sub_u32_e32 v17, v12, v13
	v_or_b32_e32 v4, v14, v4
	v_and_b32_e32 v5, 24, v5
	s_movk_i32 s8, 0x110
	v_add_u32_e32 v150, s5, v17
	v_add_u32_e32 v17, s6, v14
	v_add_u32_e32 v2, s6, v2
	v_add_u32_e32 v5, 0, v5
	v_mad_u64_u32 v[136:137], s[6:7], v15, s8, v[6:7]
	v_mad_u64_u32 v[134:135], s[6:7], v8, s8, v[6:7]
	v_mul_u32_u24_e32 v6, 0x110, v12
	v_mul_u32_u24_e32 v8, 0x90, v12
	v_mul_u32_u24_e32 v4, 0x110, v4
	v_lshl_add_u64 v[138:139], s[0:1], 0, v[10:11]
	v_sub_u32_e32 v10, v13, v12
	v_subrev_u32_e32 v153, s5, v10
	v_add_u32_e32 v154, 64, v9
	v_add_u32_e32 v155, 64, v16
	s_movk_i32 s16, 0xffef
	v_add_u32_e32 v152, v7, v6
	v_add_u32_e32 v151, v17, v8
	v_add_u32_e32 v137, v2, v8
	v_add_u32_e32 v135, v5, v4
	v_mov_b32_e32 v156, v150
	v_mov_b32_e32 v2, v3
	v_mov_b32_e32 v4, v3
	v_mov_b32_e32 v5, v3
	v_mov_b32_e32 v6, v3
	v_mov_b32_e32 v7, v3
	v_mov_b32_e32 v8, v3
	v_mov_b32_e32 v9, v3
	v_mov_b32_e32 v10, v3
	v_mov_b32_e32 v12, v3
	v_mov_b32_e32 v13, v3
	v_mov_b32_e32 v14, v3
	v_mov_b32_e32 v15, v3
	v_mov_b32_e32 v16, v3
	v_mov_b32_e32 v17, v3
	v_mov_b32_e32 v18, v3
	v_mov_b32_e32 v19, v3
	v_mov_b32_e32 v20, v3
	v_readlane_b32 s30, v242, 14
	v_readlane_b32 s31, v242, 15

.LBB0_406:
	s_getreg_b32 s98, hwreg(HW_REG_XCC_ID, 0, 4)
	v_mov_b32_e32 v1, 0x21160
	ds_read_b64 v[2:3], v1
	s_lshl_b32 s98, s98, 8
	s_add_u32 s100, s54, 0x5400
	s_addc_u32 s101, s55, 0
	v_mov_b32_e32 v4, s98
	v_mov_b32_e32 v5, 1
	global_atomic_add v4, v4, v5, s[100:101] sc0
	s_waitcnt lgkmcnt(0)
	v_mul_u32_u24_e32 v2, 4, v2
	v_mul_u32_u24_e32 v3, 4, v3
	s_waitcnt vmcnt(0)
	v_add_u32_e32 v4, 1, v4
	v_cmp_eq_u32_e32 vcc, v4, v2
	s_and_saveexec_b64 s[98:99], vcc
	s_cbranch_execz .Lgbar4_poll
	buffer_wbl2 sc1
	s_waitcnt vmcnt(0)
	v_mov_b32_e32 v4, 0x7400
	global_atomic_add v4, v5, s[54:55]

.Lgbar4_done:
	buffer_inv sc1
	s_waitcnt vmcnt(0)
.LBB0_442:
	s_or_b64 exec, exec, s[6:7]
	v_readlane_b32 s0, v242, 38
	s_add_u32 s84, s54, 0x3400000
	v_mov_b32_e32 v215, v0
	v_readlane_b32 s1, v242, 39
	s_addc_u32 s85, s55, 0
	s_waitcnt lgkmcnt(0)
	s_barrier
	s_and_b64 vcc, exec, s[0:1]
	v_readfirstlane_b32 s3, v215
	s_cbranch_vccnz .LBB0_497
	v_lshlrev_b32_e32 v1, 4, v215
	v_add_u32_e32 v2, 0x2000, v1
	v_ashrrev_i32_e32 v3, 31, v2
	v_lshrrev_b32_e32 v3, 22, v3
	v_add_u32_e32 v3, v2, v3
	v_ashrrev_i32_e32 v10, 10, v3
	v_mul_i32_i24_e32 v3, 0x400, v10
	v_sub_u32_e32 v2, v2, v3
	v_lshrrev_b32_e32 v3, 4, v2
	v_bitop3_b32 v2, v3, v2, 32 bitop3:0x6c
	v_ashrrev_i32_e32 v3, 31, v2
	v_lshrrev_b32_e32 v3, 26, v3
	v_add_u32_e32 v3, v2, v3
	v_lshlrev_b32_e32 v4, 3, v10
	v_ashrrev_i32_e32 v11, 6, v3
	v_and_b32_e32 v4, -16, v4
	v_add_u32_e32 v4, v11, v4
	v_and_b32_e32 v5, 3, v11
	s_mov_b32 s0, 0x1fffe0
	v_lshrrev_b32_e32 v6, 2, v4
	v_lshlrev_b32_e32 v7, 1, v4
	v_and_b32_e32 v3, 0xc0, v3
	v_and_or_b32 v5, v4, s0, v5
	v_and_b32_e32 v6, 4, v6
	v_and_b32_e32 v7, 24, v7
	v_sub_u32_e32 v2, v2, v3
	v_mov_b32_e32 v3, 1
	v_or3_b32 v5, v5, v6, v7
	v_lshlrev_b32_e32 v6, 5, v10
	v_ashrrev_i16_sdwa v2, v3, sext(v2) dst_sel:DWORD dst_unused:UNUSED_PAD src0_sel:DWORD src1_sel:BYTE_0
	v_and_b32_e32 v6, 32, v6
	v_bfe_i32 v12, v2, 0, 16
	v_add_lshl_u32 v2, v6, v12, 1
	v_lshl_add_u32 v130, v5, 11, v2
	v_lshl_add_u32 v132, v4, 11, v2
	v_bfe_i32 v2, v215, 27, 1
	v_lshrrev_b32_e32 v2, 22, v2
	v_add_u32_e32 v2, v1, v2
	v_and_b32_e32 v2, 0xfffffc00, v2
	v_sub_u32_e32 v1, v1, v2
	v_lshrrev_b32_e32 v2, 4, v1
	v_ashrrev_i32_e32 v4, 31, v215
	v_bitop3_b32 v1, v2, v1, 32 bitop3:0x6c
	v_lshrrev_b32_e32 v4, 26, v4
	v_ashrrev_i32_e32 v2, 31, v1
	v_add_u32_e32 v4, v215, v4
	v_lshrrev_b32_e32 v2, 26, v2
	v_ashrrev_i32_e32 v14, 6, v4
	v_add_u32_e32 v2, v1, v2
	v_lshlrev_b32_e32 v4, 3, v14
	v_ashrrev_i32_e32 v13, 6, v2
	v_and_b32_e32 v4, -16, v4
	v_add_u32_e32 v4, v13, v4
	v_and_b32_e32 v5, 3, v13
	s_ashr_i32 s62, s38, 31
	v_and_or_b32 v5, v4, s0, v5
	s_lshr_b32 s0, s62, 29
	s_add_i32 s0, s38, s0
	s_ashr_i32 s34, s3, 6
	s_ashr_i32 s1, s0, 3
	s_and_b32 s0, s0, -8
	s_ashr_i32 s4, s3, 8
	s_lshl_b32 s37, s34, 10
	s_sub_i32 s0, s38, s0
	s_cmp_lt_i32 s0, 0
	s_cselect_b32 s5, 25, 24
	s_mul_i32 s0, s0, s5
	s_add_i32 s0, s0, s1
	s_mul_hi_i32 s1, s0, 0x2aaaaaab
	s_lshr_b32 s5, s1, 31
	s_ashr_i32 s1, s1, 2
	s_add_i32 s1, s1, s5
	s_mul_i32 s5, s1, 6
	s_mul_i32 s1, s1, 24
	s_sub_i32 s0, s0, s1
	s_bfe_i32 s1, s0, 0x80000
	s_mul_i32 s1, s1, 43
	s_bfe_u32 s6, s1, 0x1000f
	s_bfe_u32 s1, s1, 0x80008
	s_add_i32 s6, s1, s6
	s_mul_i32 s1, s6, 6
	s_sub_i32 s0, s0, s1
	s_sext_i32_i8 s0, s0
	v_lshrrev_b32_e32 v6, 2, v4
	v_lshlrev_b32_e32 v7, 1, v4
	v_and_b32_e32 v2, 0xc0, v2
	s_add_i32 s86, s5, s0
	v_and_b32_e32 v6, 4, v6
	v_and_b32_e32 v7, 24, v7
	v_sub_u32_e32 v1, v1, v2
	s_ashr_i32 s87, s86, 31
	s_bfe_i64 s[8:9], s[6:7], 0x80000
	v_or3_b32 v5, v5, v6, v7
	v_lshlrev_b32_e32 v6, 5, v14
	v_ashrrev_i16_sdwa v1, v3, sext(v1) dst_sel:DWORD dst_unused:UNUSED_PAD src0_sel:DWORD src1_sel:BYTE_0
	s_lshl_b64 s[0:1], s[86:87], 19
	s_lshl_b64 s[8:9], s[8:9], 19
	v_and_b32_e32 v6, 32, v6
	v_bfe_i32 v15, v1, 0, 16
	s_add_u32 s26, s70, s8
	v_add_lshl_u32 v1, v6, v15, 1
	s_addc_u32 s27, s71, s9
	s_add_i32 s63, s37, 0
	v_lshl_add_u32 v134, v5, 11, v1
	s_add_i32 m0, s63, 0x10000
	v_lshl_add_u32 v136, v4, 11, v1
	global_load_lds_dwordx4 v134, s[26:27]
	s_add_i32 m0, s63, 0x12000
	s_add_u32 s8, s26, 0x40000
	global_load_lds_dwordx4 v130, s[26:27]
	s_addc_u32 s9, s27, 0
	s_add_i32 m0, s63, 0x14000
	v_mov_b32_e32 v135, 0
	global_load_lds_dwordx4 v134, s[8:9]
	s_add_i32 m0, s63, 0x16000
	s_add_u32 s10, s60, s0
	s_addc_u32 s11, s61, s1
	s_add_i32 s0, s63, 0x2000
	global_load_lds_dwordx4 v130, s[8:9]
	s_mov_b32 m0, s63
	s_add_u32 s8, s10, 0x40000
	global_load_lds_dwordx4 v136, s[10:11]
	s_mov_b32 m0, s0
	s_addc_u32 s9, s11, 0
	s_add_i32 s1, s63, 0x4000
	global_load_lds_dwordx4 v132, s[10:11]
	s_mov_b32 m0, s1
	s_add_i32 s64, s63, 0x6000
	global_load_lds_dwordx4 v136, s[8:9]
	s_mov_b32 m0, s64
	v_mov_b32_e32 v131, v135
	global_load_lds_dwordx4 v132, s[8:9]
	v_mov_b32_e32 v137, v135
	v_mov_b32_e32 v133, v135
	s_mov_b32 s65, 0
	v_lshl_add_u64 v[8:9], s[26:27], 0, v[134:135]
	v_lshl_add_u64 v[6:7], s[26:27], 0, v[130:131]
	v_lshl_add_u64 v[4:5], s[10:11], 0, v[136:137]
	s_cmp_lg_u32 s4, 1
	v_lshl_add_u64 v[2:3], s[10:11], 0, v[132:133]
	s_cbranch_scc1 .LBB0_445
	s_barrier

.LBB0_536:
	s_getreg_b32 s98, hwreg(HW_REG_XCC_ID, 0, 4)
	v_mov_b32_e32 v1, 0x21160
	ds_read_b64 v[2:3], v1
	s_lshl_b32 s98, s98, 8
	s_add_u32 s100, s54, 0x5400
	s_addc_u32 s101, s55, 0
	v_mov_b32_e32 v4, s98
	v_mov_b32_e32 v5, 1
	global_atomic_add v4, v4, v5, s[100:101] sc0
	s_waitcnt lgkmcnt(0)
	v_mul_u32_u24_e32 v2, 5, v2
	v_mul_u32_u24_e32 v3, 5, v3
	s_waitcnt vmcnt(0)
	v_add_u32_e32 v4, 1, v4
	v_cmp_eq_u32_e32 vcc, v4, v2
	s_and_saveexec_b64 s[98:99], vcc
	s_cbranch_execz .Lgbar5_poll
	buffer_wbl2 sc1
	s_waitcnt vmcnt(0)
	v_mov_b32_e32 v4, 0x7400
	global_atomic_add v4, v5, s[54:55]

.Lgbar5_done:
	buffer_inv sc1
	s_waitcnt vmcnt(0)
.LBB0_572:
	s_or_b64 exec, exec, s[6:7]
	v_mov_b32_e32 v12, v0
	s_waitcnt lgkmcnt(0)
	s_barrier
	s_cmpk_gt_i32 s38, 0x2ff
	v_readfirstlane_b32 s4, v12
	s_cbranch_scc1 .LBB0_588
	v_lshlrev_b32_e32 v1, 4, v12
	v_add_u32_e32 v2, 0x2000, v1
	v_ashrrev_i32_e32 v3, 31, v2
	v_lshrrev_b32_e32 v3, 22, v3
	v_add_u32_e32 v3, v2, v3
	v_ashrrev_i32_e32 v10, 10, v3
	v_mul_i32_i24_e32 v3, 0x400, v10
	v_sub_u32_e32 v2, v2, v3
	v_lshrrev_b32_e32 v3, 4, v2
	v_bitop3_b32 v2, v3, v2, 32 bitop3:0x6c
	v_ashrrev_i32_e32 v3, 31, v2
	v_lshrrev_b32_e32 v3, 26, v3
	v_add_u32_e32 v3, v2, v3
	v_lshlrev_b32_e32 v4, 3, v10
	v_ashrrev_i32_e32 v11, 6, v3
	v_and_b32_e32 v4, -16, v4
	v_add_u32_e32 v4, v11, v4
	v_and_b32_e32 v5, 3, v11
	s_mov_b32 s0, 0x1fffe0
	v_lshrrev_b32_e32 v6, 2, v4
	v_lshlrev_b32_e32 v7, 1, v4
	v_and_b32_e32 v3, 0xc0, v3
	v_and_or_b32 v5, v4, s0, v5
	v_and_b32_e32 v6, 4, v6
	v_and_b32_e32 v7, 24, v7
	v_sub_u32_e32 v2, v2, v3
	v_mov_b32_e32 v3, 1
	v_or3_b32 v5, v5, v6, v7
	v_lshlrev_b32_e32 v6, 5, v10
	v_ashrrev_i16_sdwa v2, v3, sext(v2) dst_sel:DWORD dst_unused:UNUSED_PAD src0_sel:DWORD src1_sel:BYTE_0
	v_and_b32_e32 v6, 32, v6
	v_bfe_i32 v13, v2, 0, 16
	v_add_lshl_u32 v2, v6, v13, 1
	v_lshl_add_u32 v146, v5, 11, v2
	v_lshl_add_u32 v148, v4, 11, v2
	v_bfe_i32 v2, v12, 27, 1
	v_lshrrev_b32_e32 v2, 22, v2
	v_add_u32_e32 v2, v1, v2
	v_and_b32_e32 v2, 0xfffffc00, v2
	v_sub_u32_e32 v1, v1, v2
	v_lshrrev_b32_e32 v2, 4, v1
	v_ashrrev_i32_e32 v4, 31, v12
	v_bitop3_b32 v1, v2, v1, 32 bitop3:0x6c
	v_lshrrev_b32_e32 v4, 26, v4
	v_ashrrev_i32_e32 v2, 31, v1
	v_add_u32_e32 v4, v12, v4
	v_lshrrev_b32_e32 v2, 26, v2
	v_ashrrev_i32_e32 v15, 6, v4
	v_add_u32_e32 v2, v1, v2
	v_lshlrev_b32_e32 v4, 3, v15
	v_ashrrev_i32_e32 v14, 6, v2
	v_and_b32_e32 v4, -16, v4
	v_add_u32_e32 v4, v14, v4
	v_and_b32_e32 v5, 3, v14
	v_and_or_b32 v5, v4, s0, v5
	s_ashr_i32 s0, s38, 31
	s_lshr_b32 s1, s0, 29
	s_add_i32 s1, s38, s1
	s_ashr_i32 s7, s4, 6
	s_ashr_i32 s6, s1, 3
	s_and_b32 s1, s1, -8
	s_ashr_i32 s5, s4, 8
	s_lshl_b32 s3, s7, 10
	s_sub_i32 s14, s38, s1
	s_cmp_lt_i32 s14, 0
	s_movk_i32 s1, 0x61
	s_cselect_b32 s15, s1, 0x60
	s_mul_i32 s14, s14, s15
	s_add_i32 s14, s14, s6
	s_mul_hi_i32 s6, s14, 0x2aaaaaab
	s_lshr_b32 s15, s6, 31
	s_ashr_i32 s6, s6, 4
	s_add_i32 s6, s6, s15
	s_mul_i32 s15, s6, 6
	s_mulk_i32 s6, 0x60
	s_sub_i32 s14, s14, s6
	s_bfe_i32 s6, s14, 0x80000
	s_mul_i32 s6, s6, 43
	s_bfe_u32 s16, s6, 0x1000f
	s_bfe_u32 s6, s6, 0x80008
	s_add_i32 s6, s6, s16
	s_mul_i32 s16, s6, 6
	s_sub_i32 s14, s14, s16
	s_sext_i32_i8 s14, s14
	v_lshrrev_b32_e32 v6, 2, v4
	v_lshlrev_b32_e32 v7, 1, v4
	v_and_b32_e32 v2, 0xc0, v2
	s_add_i32 s40, s15, s14
	v_and_b32_e32 v6, 4, v6
	v_and_b32_e32 v7, 24, v7
	v_sub_u32_e32 v1, v1, v2
	s_ashr_i32 s41, s40, 31
	s_bfe_i64 s[16:17], s[6:7], 0x80000
	v_or3_b32 v5, v5, v6, v7
	v_lshlrev_b32_e32 v6, 5, v15
	v_ashrrev_i16_sdwa v1, v3, sext(v1) dst_sel:DWORD dst_unused:UNUSED_PAD src0_sel:DWORD src1_sel:BYTE_0
	s_lshl_b64 s[14:15], s[40:41], 19
	s_lshl_b64 s[16:17], s[16:17], 19
	v_and_b32_e32 v6, 32, v6
	v_bfe_i32 v16, v1, 0, 16
	s_add_u32 s56, s88, s16
	v_add_lshl_u32 v1, v6, v16, 1
	s_addc_u32 s57, s89, s17
	s_add_i32 s41, s3, 0
	v_lshl_add_u32 v150, v5, 11, v1
	s_add_i32 m0, s41, 0x10000
	v_lshl_add_u32 v152, v4, 11, v1
	global_load_lds_dwordx4 v150, s[56:57]
	s_add_i32 m0, s41, 0x12000
	s_add_u32 s16, s56, 0x40000
	global_load_lds_dwordx4 v146, s[56:57]
	s_addc_u32 s17, s57, 0
	s_add_i32 m0, s41, 0x14000
	v_mov_b32_e32 v151, 0
	global_load_lds_dwordx4 v150, s[16:17]
	s_add_i32 m0, s41, 0x16000
	s_add_u32 s44, s66, s14
	s_addc_u32 s45, s67, s15
	s_add_i32 s60, s41, 0x2000
	global_load_lds_dwordx4 v146, s[16:17]
	s_mov_b32 m0, s41
	s_add_u32 s14, s44, 0x40000
	global_load_lds_dwordx4 v152, s[44:45]
	s_mov_b32 m0, s60
	s_addc_u32 s15, s45, 0
	s_add_i32 s61, s41, 0x4000
	global_load_lds_dwordx4 v148, s[44:45]
	s_mov_b32 m0, s61
	s_add_i32 s62, s41, 0x6000
	global_load_lds_dwordx4 v152, s[14:15]
	s_mov_b32 m0, s62
	v_mov_b32_e32 v147, v151
	global_load_lds_dwordx4 v148, s[14:15]
	v_mov_b32_e32 v153, v151
	v_mov_b32_e32 v149, v151
	s_cmp_eq_u32 s5, 1
	s_mov_b32 s63, 0
	v_lshl_add_u64 v[8:9], s[56:57], 0, v[150:151]
	v_lshl_add_u64 v[6:7], s[56:57], 0, v[146:147]
	v_lshl_add_u64 v[2:3], s[44:45], 0, v[152:153]
	s_cselect_b64 s[14:15], -1, 0
	s_cmp_lg_u32 s5, 1
	v_lshl_add_u64 v[4:5], s[44:45], 0, v[148:149]
	s_cbranch_scc1 .LBB0_575
	s_barrier

.LBB0_604:
	s_getreg_b32 s98, hwreg(HW_REG_XCC_ID, 0, 4)
	v_mov_b32_e32 v1, 0x21160
	ds_read_b64 v[2:3], v1
	s_lshl_b32 s98, s98, 8
	s_add_u32 s100, s54, 0x5400
	s_addc_u32 s101, s55, 0
	v_mov_b32_e32 v4, s98
	v_mov_b32_e32 v5, 1
	global_atomic_add v4, v4, v5, s[100:101] sc0
	s_waitcnt lgkmcnt(0)
	v_mul_u32_u24_e32 v2, 6, v2
	v_mul_u32_u24_e32 v3, 6, v3
	s_waitcnt vmcnt(0)
	v_add_u32_e32 v4, 1, v4
	v_cmp_eq_u32_e32 vcc, v4, v2
	s_and_saveexec_b64 s[98:99], vcc
	s_cbranch_execz .Lgbar6_poll
	buffer_wbl2 sc1
	s_waitcnt vmcnt(0)
	v_mov_b32_e32 v4, 0x7400
	global_atomic_add v4, v5, s[54:55]

.Lgbar6_done:
	buffer_inv sc1
	s_waitcnt vmcnt(0)
.LBB0_640:
	s_or_b64 exec, exec, s[6:7]
	v_readlane_b32 s0, v242, 38
	v_readlane_b32 s1, v242, 39
	s_waitcnt lgkmcnt(0)
	s_barrier
	s_and_b64 vcc, exec, s[0:1]
	v_readfirstlane_b32 s34, v0
	v_lshlrev_b32_e32 v1, 4, v0
	v_add_u32_e32 v2, 0x2000, v1
	v_ashrrev_i32_e32 v3, 31, v2
	v_lshrrev_b32_e32 v3, 22, v3
	v_add_u32_e32 v3, v2, v3
	v_ashrrev_i32_e32 v10, 10, v3
	v_mul_i32_i24_e32 v3, 0x400, v10
	v_sub_u32_e32 v2, v2, v3
	v_lshrrev_b32_e32 v3, 4, v2
	v_bitop3_b32 v2, v3, v2, 32 bitop3:0x6c
	v_ashrrev_i32_e32 v3, 31, v2
	v_lshrrev_b32_e32 v3, 26, v3
	v_add_u32_e32 v3, v2, v3
	v_lshlrev_b32_e32 v4, 3, v10
	v_ashrrev_i32_e32 v11, 6, v3
	v_and_b32_e32 v4, -16, v4
	v_add_u32_e32 v4, v11, v4
	v_and_b32_e32 v5, 3, v11
	s_mov_b32 s0, 0x7ffe0
	v_lshrrev_b32_e32 v6, 2, v4
	v_lshlrev_b32_e32 v7, 1, v4
	v_and_b32_e32 v3, 0xc0, v3
	v_and_or_b32 v5, v4, s0, v5
	v_and_b32_e32 v6, 4, v6
	v_and_b32_e32 v7, 24, v7
	v_sub_u32_e32 v2, v2, v3
	v_mov_b32_e32 v3, 1
	v_or3_b32 v5, v5, v6, v7
	v_lshlrev_b32_e32 v6, 5, v10
	v_ashrrev_i16_sdwa v2, v3, sext(v2) dst_sel:DWORD dst_unused:UNUSED_PAD src0_sel:DWORD src1_sel:BYTE_0
	v_and_b32_e32 v6, 32, v6
	v_bfe_i32 v12, v2, 0, 16
	v_add_lshl_u32 v2, v6, v12, 1
	v_lshl_add_u32 v122, v5, 13, v2
	v_lshl_add_u32 v124, v4, 13, v2
	v_add_u32_e32 v124, 0xfffe0000, v124
	v_bfe_i32 v2, v0, 27, 1
	v_lshrrev_b32_e32 v2, 22, v2
	v_add_u32_e32 v2, v1, v2
	v_and_b32_e32 v2, 0xfffffc00, v2
	v_sub_u32_e32 v1, v1, v2
	v_lshrrev_b32_e32 v2, 4, v1
	v_ashrrev_i32_e32 v4, 31, v0
	v_bitop3_b32 v1, v2, v1, 32 bitop3:0x6c
	v_lshrrev_b32_e32 v4, 26, v4
	v_ashrrev_i32_e32 v2, 31, v1
	v_add_u32_e32 v4, v0, v4
	v_lshrrev_b32_e32 v2, 26, v2
	v_ashrrev_i32_e32 v14, 6, v4
	v_add_u32_e32 v2, v1, v2
	v_lshlrev_b32_e32 v4, 3, v14
	v_ashrrev_i32_e32 v13, 6, v2
	v_and_b32_e32 v4, -16, v4
	v_add_u32_e32 v4, v13, v4
	v_and_b32_e32 v5, 3, v13
	s_ashr_i32 s36, s38, 31
	v_and_or_b32 v5, v4, s0, v5
	s_lshr_b32 s0, s36, 29
	s_add_i32 s0, s38, s0
	s_ashr_i32 s3, s34, 6
	s_ashr_i32 s1, s0, 3
	s_and_b32 s0, s0, -8
	s_ashr_i32 s11, s34, 8
	s_lshl_b32 s35, s3, 10
	s_sub_i32 s0, s38, s0
	s_cmp_lt_i32 s0, 0
	s_cselect_b32 s4, 25, 24
	s_mul_i32 s0, s0, s4
	s_add_i32 s0, s0, s1
	s_mul_hi_i32 s1, s0, 0x2aaaaaab
	s_lshr_b32 s4, s1, 31
	s_ashr_i32 s1, s1, 2
	s_add_i32 s1, s1, s4
	s_mul_i32 s4, s1, 6
	s_mul_i32 s1, s1, 24
	s_sub_i32 s1, s0, s1
	s_mul_i32 s0, s1, 43
	s_bfe_u32 s5, s0, 0x1000f
	s_bfe_u32 s0, s0, 0x80008
	s_add_i32 s0, s0, s5
	s_mul_i32 s5, s0, 6
	s_sub_i32 s1, s1, s5
	s_sext_i32_i8 s1, s1
	v_lshrrev_b32_e32 v6, 2, v4
	v_lshlrev_b32_e32 v7, 1, v4
	v_and_b32_e32 v2, 0xc0, v2
	s_add_i32 s6, s4, s1
	v_and_b32_e32 v6, 4, v6
	v_and_b32_e32 v7, 24, v7
	v_sub_u32_e32 v1, v1, v2
	s_lshr_b32 s1, s38, 3
	s_and_b32 s0, s1, 3
	s_lshr_b32 s1, s1, 2
	s_and_b32 s6, s38, 7
	s_lshl_b32 s6, s6, 3
	s_add_i32 s6, s6, s1
	s_ashr_i32 s7, s6, 31
	s_bfe_i64 s[14:15], s[0:1], 0x80000
	v_or3_b32 v5, v5, v6, v7
	v_lshlrev_b32_e32 v6, 5, v14
	v_ashrrev_i16_sdwa v1, v3, sext(v1) dst_sel:DWORD dst_unused:UNUSED_PAD src0_sel:DWORD src1_sel:BYTE_0
	s_mul_i32 s4, s6, 0x180000
	s_mov_b32 s5, 0
	s_lshl_b64 s[14:15], s[14:15], 21
	v_and_b32_e32 v6, 32, v6
	v_bfe_i32 v15, v1, 0, 16
	s_add_u32 s26, s86, s14
	v_add_lshl_u32 v1, v6, v15, 1
	s_addc_u32 s27, s87, s15
	s_add_i32 s37, s35, 0
	v_lshl_add_u32 v134, v5, 13, v1
	s_add_i32 m0, s37, 0x10000
	v_lshl_add_u32 v136, v4, 13, v1
	global_load_lds_dwordx4 v134, s[26:27]
	s_add_i32 m0, s37, 0x12000
	s_add_u32 s14, s26, 0x100000
	global_load_lds_dwordx4 v122, s[26:27]
	s_addc_u32 s15, s27, 0
	s_add_i32 m0, s37, 0x14000
	v_mov_b32_e32 v135, 0
	global_load_lds_dwordx4 v134, s[14:15]
	s_add_i32 m0, s37, 0x16000
	v_mov_b32_e32 v123, v135
	global_load_lds_dwordx4 v122, s[14:15]
	s_add_u32 s14, s68, s4
	s_addc_u32 s15, s69, s5
	s_add_i32 s41, s37, 0x2000
	s_mov_b32 m0, s37
	s_add_u32 s4, s14, 0xc0000
	global_load_lds_dwordx4 v136, s[14:15]
	s_mov_b32 m0, s41
	s_addc_u32 s5, s15, 0
	s_add_i32 s42, s37, 0x4000
	global_load_lds_dwordx4 v124, s[14:15]
	s_mov_b32 m0, s42
	s_add_i32 s43, s37, 0x6000
	global_load_lds_dwordx4 v136, s[4:5]
	s_mov_b32 m0, s43
	v_mov_b32_e32 v137, v135
	global_load_lds_dwordx4 v124, s[4:5]
	v_mov_b32_e32 v125, v135
	s_mov_b32 s44, 0
	v_lshl_add_u64 v[8:9], s[26:27], 0, v[134:135]
	v_lshl_add_u64 v[6:7], s[26:27], 0, v[122:123]
	v_lshl_add_u64 v[4:5], s[14:15], 0, v[136:137]
	s_cmp_lg_u32 s11, 1
	v_lshl_add_u64 v[2:3], s[14:15], 0, v[124:125]
	s_cbranch_scc1 .LBB0_643
	s_barrier
